# grid barrier: wave 1 of every workgroup issues an un-waited buffer_wbl2 once its workgroup's stores are drained, pre-cleaning the XCD L2 ahead of the leader's release flush
# baseline (speedup 1.0000x reference)
; __device__ __forceinline__ unsigned xb_add(unsigned* p, unsigned v) { return __hip_atomic_fetch_add(p, v, __ATOMIC_RELAXED, __HIP_MEMORY_SCOPE_AGENT); }
; __device__ __forceinline__ void xcd_barrier(const XcdBarrier& b) {
;     asm volatile("s_waitcnt vmcnt(0)" ::: "memory");
;     __syncthreads();
;     if (threadIdx.x == 0) {
;         unsigned* bar = b.bar;
;         __builtin_amdgcn_s_waitcnt(0);
;         unsigned nloc = b.st[0], nx = b.st[1];
;         if (nloc == 0u) { xcd_barrier_complete(bar, b.x, nloc, nx); b.st[0] = nloc; b.st[1] = nx; }
;         const unsigned old = xb_add(&bar[XB_XSUB(b.x)], 1u);
.LBB0_88:
	s_waitcnt vmcnt(0)
	s_waitcnt lgkmcnt(0)
	s_barrier
	v_cmp_eq_u32_e32 vcc, 64, v208
	s_and_saveexec_b64 s[0:1], vcc
	s_cbranch_execz .Lwbpre_1
	buffer_wbl2 sc1
.Lwbpre_1:
	s_mov_b64 exec, s[0:1]
	s_and_saveexec_b64 s[0:1], s[80:81]
	s_cbranch_execz .LBB0_140
	v_readlane_b32 s3, v252, 23
	s_waitcnt vmcnt(0) expcnt(0) lgkmcnt(0)
	s_nop 0
	v_mov_b32_e32 v0, s3
	ds_read_b32 v3, v0
	v_readlane_b32 s3, v252, 24
	s_waitcnt lgkmcnt(0)
	v_cmp_ne_u32_e32 vcc, 0, v3
	v_mov_b32_e32 v0, s3
	ds_read_b32 v2, v0
	s_cbranch_vccnz .LBB0_104
	s_mov_b32 s4, 1
	s_branch .LBB0_92

; __device__ __forceinline__ unsigned xb_add(unsigned* p, unsigned v) { return __hip_atomic_fetch_add(p, v, __ATOMIC_RELAXED, __HIP_MEMORY_SCOPE_AGENT); }
; __device__ __forceinline__ void xcd_barrier(const XcdBarrier& b) {
;     asm volatile("s_waitcnt vmcnt(0)" ::: "memory");
;     __syncthreads();
;     if (threadIdx.x == 0) {
;         unsigned* bar = b.bar;
;         __builtin_amdgcn_s_waitcnt(0);
;         unsigned nloc = b.st[0], nx = b.st[1];
;         if (nloc == 0u) { xcd_barrier_complete(bar, b.x, nloc, nx); b.st[0] = nloc; b.st[1] = nx; }
;         const unsigned old = xb_add(&bar[XB_XSUB(b.x)], 1u);
.LBB0_262:
	s_waitcnt vmcnt(0)
	s_barrier
	v_cmp_eq_u32_e32 vcc, 64, v208
	s_and_saveexec_b64 s[0:1], vcc
	s_cbranch_execz .Lwbpre_2
	buffer_wbl2 sc1
.Lwbpre_2:
	s_mov_b64 exec, s[0:1]
	s_and_saveexec_b64 s[0:1], s[80:81]
	s_cbranch_execz .LBB0_314
	v_readlane_b32 s4, v252, 23
	s_waitcnt vmcnt(0) expcnt(0) lgkmcnt(0)
	s_nop 0
	v_mov_b32_e32 v0, s4
	ds_read_b32 v3, v0
	v_readlane_b32 s4, v252, 24
	s_waitcnt lgkmcnt(0)
	v_cmp_ne_u32_e32 vcc, 0, v3
	v_mov_b32_e32 v0, s4
	ds_read_b32 v2, v0
	s_cbranch_vccnz .LBB0_278
	s_mov_b32 s4, 1
	s_branch .LBB0_266

; __device__ __forceinline__ void xcd_barrier(const XcdBarrier& b) {
;     ...
;     if (threadIdx.x == 0) {
;         unsigned* bar = b.bar;
;         __builtin_amdgcn_s_waitcnt(0);
;         unsigned nloc = b.st[0], nx = b.st[1];
;         if (nloc == 0u) { xcd_barrier_complete(bar, b.x, nloc, nx); b.st[0] = nloc; b.st[1] = nx; }
.Lwbpre_6:
	s_mov_b64 exec, s[0:1]
	s_and_saveexec_b64 s[0:1], s[80:81]
	v_readlane_b32 s12, v252, 28
	v_readlane_b32 s13, v252, 29
	s_cbranch_execz .LBB0_859
	v_readlane_b32 s4, v252, 23
	s_waitcnt vmcnt(0) expcnt(0) lgkmcnt(0)
	s_nop 0
	v_mov_b32_e32 v0, s4
	ds_read_b32 v3, v0
	v_readlane_b32 s4, v252, 24
	s_waitcnt lgkmcnt(0)
	v_cmp_ne_u32_e32 vcc, 0, v3
	v_mov_b32_e32 v0, s4
	ds_read_b32 v2, v0
	s_cbranch_vccnz .LBB0_823
	s_mov_b32 s4, 1
	s_branch .LBB0_811

; __device__ __forceinline__ void xcd_barrier(const XcdBarrier& b) {
;     asm volatile("s_waitcnt vmcnt(0)" ::: "memory");
;     __syncthreads();
;     if (threadIdx.x == 0) {
.LBB0_866:
	s_or_b64 exec, exec, s[0:1]
	s_waitcnt vmcnt(0)
	s_barrier
	v_cmp_eq_u32_e32 vcc, 64, v208
	s_and_saveexec_b64 s[0:1], vcc
	s_cbranch_execz .Lwbpre_7
	buffer_wbl2 sc1
